# P5 H.C MFMA chain: LDS fragments read 5-6 MFMAs ahead into spare VGPR quads
# baseline (speedup 1.0000x reference)
.LBB0_832:
	s_bitcmp1_b32 s87, 0
	s_cselect_b32 vcc_lo, 0x8800, 0
	v_add_u32_e32 v147, vcc_lo, v194
	v_add_u32_e32 v66, s33, v141
	v_add_u32_e32 v149, v147, v204
	global_load_dwordx2 v[168:169], v[160:161], off offset:-64
	global_load_dwordx2 v[166:167], v[160:161], off offset:-32
	global_load_dwordx2 v[164:165], v[160:161], off
	global_load_dwordx2 v[162:163], v[160:161], off offset:32
	ds_read_b32 v145, v66
	ds_read_b128 v[198:201], v149 offset:8256
	ds_read_b128 v[66:69], v149 offset:8192
	ds_read_b128 v[70:73], v149 offset:12544
	ds_read_b128 v[74:77], v149 offset:16896
	ds_read_b128 v[78:81], v149 offset:21248
	ds_read_b128 v[224:227], v149 offset:12608
	ds_read_b128 v[228:231], v149 offset:16960
	ds_read_b128 v[232:235], v149 offset:21312
	ds_read_b128 v[236:239], v149 offset:8320
	ds_read_b128 v[240:243], v149 offset:12672
	global_load_dword v170, v[150:151], off
	s_waitcnt lgkmcnt(8)
	v_mfma_f32_16x16x32_bf16 v[66:69], v[66:69], v[18:21], 0
	v_add_u32_e32 v220, v147, v96
	v_add_u32_e32 v147, s33, v187
	s_andn2_b64 vcc, exec, s[78:79]
	v_mfma_f32_16x16x32_bf16 v[66:69], v[198:201], v[22:25], v[66:69]
	ds_read_b128 v[198:201], v149 offset:17024
	s_waitcnt lgkmcnt(8)
	v_mfma_f32_16x16x32_bf16 v[70:73], v[70:73], v[18:21], 0
	s_waitcnt lgkmcnt(5)
	v_mfma_f32_16x16x32_bf16 v[70:73], v[224:227], v[22:25], v[70:73]
	ds_read_b128 v[224:227], v149 offset:21376
	v_mfma_f32_16x16x32_bf16 v[74:77], v[74:77], v[18:21], 0
	s_waitcnt lgkmcnt(5)
	v_mfma_f32_16x16x32_bf16 v[74:77], v[228:231], v[22:25], v[74:77]
	ds_read_b128 v[228:231], v149 offset:8384
	v_mfma_f32_16x16x32_bf16 v[78:81], v[78:81], v[18:21], 0
	s_waitcnt lgkmcnt(5)
	v_mfma_f32_16x16x32_bf16 v[78:81], v[232:235], v[22:25], v[78:81]
	ds_read_b128 v[232:235], v149 offset:12736
	s_waitcnt lgkmcnt(5)
	v_mfma_f32_16x16x32_bf16 v[66:69], v[236:239], v[26:29], v[66:69]
	ds_read_b128 v[236:239], v149 offset:17088
	s_waitcnt lgkmcnt(5)
	v_mfma_f32_16x16x32_bf16 v[70:73], v[240:243], v[26:29], v[70:73]
	ds_read_b128 v[240:243], v149 offset:21440
	s_waitcnt lgkmcnt(5)
	v_mfma_f32_16x16x32_bf16 v[74:77], v[198:201], v[26:29], v[74:77]
	s_waitcnt lgkmcnt(4)
	v_mfma_f32_16x16x32_bf16 v[78:81], v[224:227], v[26:29], v[78:81]
	s_waitcnt lgkmcnt(3)
	v_mfma_f32_16x16x32_bf16 v[198:201], v[228:231], v[30:33], v[66:69]
	s_waitcnt lgkmcnt(2)
	v_mfma_f32_16x16x32_bf16 v[70:73], v[232:235], v[30:33], v[70:73]
	s_waitcnt lgkmcnt(1)
	v_mfma_f32_16x16x32_bf16 v[206:209], v[236:239], v[30:33], v[74:77]
	s_nop 2
	v_mul_f32_e32 v74, 0x3fb8aa3b, v145
	v_exp_f32_e32 v202, v74
	s_waitcnt lgkmcnt(0)
	v_mfma_f32_16x16x32_bf16 v[66:69], v[240:243], v[30:33], v[78:81]
	s_nop 2
	v_mul_f32_e64 v80, v202, v200
	v_mul_f32_e64 v81, v202, v201
	v_pk_mul_f32 v[78:79], v[202:203], v[198:199] op_sel_hi:[0,1]
	v_pk_mul_f32 v[76:77], v[202:203], v[72:73] op_sel_hi:[0,1]
	v_pk_mul_f32 v[74:75], v[202:203], v[70:71] op_sel_hi:[0,1]
	v_pk_mul_f32 v[72:73], v[202:203], v[208:209] op_sel_hi:[0,1]
	v_pk_mul_f32 v[70:71], v[202:203], v[206:207] op_sel_hi:[0,1]
	ds_read_b128 v[198:201], v147
	ds_read_b128 v[206:209], v147 offset:4096
	ds_read_b128 v[212:215], v147 offset:64
	ds_read_b128 v[216:219], v147 offset:4160
	v_pk_mul_f32 v[68:69], v[202:203], v[68:69] op_sel_hi:[0,1]
	s_waitcnt lgkmcnt(3)
	v_sub_f32_e32 v149, v145, v198
	v_sub_f32_e32 v171, v145, v199
	v_min_f32_e32 v149, 0, v149
	v_min_f32_e32 v171, 0, v171
	v_mul_f32_e32 v149, 0x3fb8aa3b, v149
	v_mul_f32_e32 v171, 0x3fb8aa3b, v171
	v_exp_f32_e32 v149, v149
	v_exp_f32_e32 v171, v171
	v_pk_mul_f32 v[66:67], v[202:203], v[66:67] op_sel_hi:[0,1]
	v_mul_f32_e32 v149, v34, v149
	v_mul_f32_e32 v171, v35, v171
	s_waitcnt lgkmcnt(2)
	v_mul_f32_e32 v149, v206, v149
	v_mul_f32_e32 v171, v207, v171
	v_cndmask_b32_e64 v199, v149, 0, s[8:9]
	v_cndmask_b32_e64 v198, 0, v171, s[10:11]
	s_waitcnt vmcnt(0)
	v_mov_b32_e32 v171, v170
	v_pk_add_f32 v[202:203], v[170:171], v[198:199] op_sel_hi:[0,1]
	v_cndmask_b32_e64 v149, v198, v202, s[14:15]
	v_cndmask_b32_e64 v202, v199, v203, s[12:13]
	v_sub_f32_e32 v198, v145, v200
	v_sub_f32_e32 v199, v145, v201
	v_min_f32_e32 v198, 0, v198
	v_min_f32_e32 v199, 0, v199
	v_mul_f32_e32 v198, 0x3fb8aa3b, v198
	v_mul_f32_e32 v199, 0x3fb8aa3b, v199
	v_exp_f32_e32 v198, v198
	v_exp_f32_e32 v199, v199
	v_cvt_pk_bf16_f32 v206, v202, v149
	v_add_u32_e32 v149, 0x6000, v220
	v_pk_mul_f32 v[198:199], v[36:37], v[198:199]
	s_nop 0
	v_pk_mul_f32 v[198:199], v[208:209], v[198:199]
	s_nop 0
	v_cndmask_b32_e64 v199, v199, 0, s[16:17]
	v_cndmask_b32_e64 v198, v198, 0, s[18:19]
	v_pk_add_f32 v[200:201], v[170:171], v[198:199] op_sel_hi:[0,1]
	v_cndmask_b32_e64 v203, v199, v201, s[20:21]
	v_cndmask_b32_e64 v207, v198, v200, s[22:23]
	s_waitcnt lgkmcnt(1)
	v_sub_f32_e32 v198, v145, v212
	v_sub_f32_e32 v199, v145, v213
	v_min_f32_e32 v198, 0, v198
	v_min_f32_e32 v199, 0, v199
	v_mul_f32_e32 v198, 0x3fb8aa3b, v198
	v_mul_f32_e32 v199, 0x3fb8aa3b, v199
	v_exp_f32_e32 v198, v198
	v_exp_f32_e32 v199, v199
	v_cvt_pk_bf16_f32 v207, v207, v203
	v_pk_mul_f32 v[198:199], v[42:43], v[198:199]
	s_waitcnt lgkmcnt(0)
	v_pk_mul_f32 v[198:199], v[216:217], v[198:199]
	s_nop 0
	v_cndmask_b32_e64 v199, v199, 0, s[24:25]
	v_cndmask_b32_e64 v198, v198, 0, s[26:27]
	v_pk_add_f32 v[200:201], v[170:171], v[198:199] op_sel_hi:[0,1]
	v_cndmask_b32_e64 v208, v199, v201, s[28:29]
	v_cndmask_b32_e64 v209, v198, v200, s[30:31]
	v_sub_f32_e32 v198, v145, v214
	v_sub_f32_e32 v199, v145, v215
	v_min_f32_e32 v198, 0, v198
	v_min_f32_e32 v199, 0, v199
	v_mul_f32_e32 v198, 0x3fb8aa3b, v198
	v_mul_f32_e32 v199, 0x3fb8aa3b, v199
	v_exp_f32_e32 v198, v198
	v_exp_f32_e32 v199, v199
	v_cvt_pk_bf16_f32 v208, v209, v208
	v_pk_mul_f32 v[198:199], v[44:45], v[198:199]
	s_nop 0
	v_pk_mul_f32 v[198:199], v[218:219], v[198:199]
	s_nop 0
	v_cndmask_b32_e64 v199, v199, 0, s[34:35]
	v_cndmask_b32_e64 v198, v198, 0, s[36:37]
	v_pk_add_f32 v[200:201], v[170:171], v[198:199] op_sel_hi:[0,1]
	v_cndmask_b32_e64 v199, v199, v201, s[38:39]
	v_cndmask_b32_e64 v198, v198, v200, s[40:41]
	v_cvt_pk_bf16_f32 v209, v198, v199
	ds_read2_b64 v[198:201], v149 offset0:128 offset1:132
	s_waitcnt lgkmcnt(0)
	v_mfma_f32_16x16x32_bf16 v[78:81], v[198:201], v[206:209], v[78:81]
	v_add_u32_e32 v198, 0x7000, v220
	ds_read2_b64 v[200:203], v198 offset0:160 offset1:164
	v_add_u32_e32 v199, 0x8000, v220
	s_waitcnt lgkmcnt(0)
	v_mfma_f32_16x16x32_bf16 v[74:77], v[200:203], v[206:209], v[74:77]
	ds_read2_b64 v[200:203], v199 offset0:192 offset1:196
	s_waitcnt lgkmcnt(0)
	v_mfma_f32_16x16x32_bf16 v[70:73], v[200:203], v[206:209], v[70:73]
	v_add_u32_e32 v200, 0x9000, v220
	ds_read2_b64 v[212:215], v200 offset0:224 offset1:228
	s_waitcnt lgkmcnt(0)
	v_mfma_f32_16x16x32_bf16 v[66:69], v[212:215], v[206:209], v[66:69]
	s_cbranch_vccz .LBB0_838
	s_andn2_b64 vcc, exec, s[80:81]
	s_cbranch_vccz .LBB0_839
